# v74 + nt on idle-round conversion stores + scan publisher priority + back-to-back barrier polls
# baseline (speedup 1.0000x reference)
.LBB0_168:
	global_load_dword v15, v16, s[10:11] sc1
	global_load_dword v0, v16, s[12:13] sc1
	global_load_dword v1, v16, s[14:15] sc1
	global_load_dword v2, v16, s[16:17] sc1
	global_load_dword v3, v16, s[18:19] sc1
	global_load_dword v4, v16, s[20:21] sc1
	global_load_dword v5, v16, s[22:23] sc1
	global_load_dword v6, v16, s[24:25] sc1
	global_load_dword v7, v16, s[26:27] sc1
	global_load_dword v8, v16, s[28:29] sc1
	global_load_dword v9, v16, s[30:31] sc1
	global_load_dword v10, v16, s[34:35] sc1
	global_load_dword v11, v16, s[36:37] sc1
	global_load_dword v12, v16, s[38:39] sc1
	global_load_dword v13, v16, s[40:41] sc1
	global_load_dword v14, v16, s[42:43] sc1
	s_mov_b64 s[48:49], -1
	s_mov_b64 s[50:51], -1
	s_waitcnt vmcnt(14)
	v_add_u32_e32 v17, v0, v15
	s_waitcnt vmcnt(13)
	v_add_u32_e32 v17, v17, v1
	s_waitcnt vmcnt(12)
	v_add_u32_e32 v17, v17, v2
	s_waitcnt vmcnt(11)
	v_add_u32_e32 v17, v17, v3
	s_waitcnt vmcnt(10)
	v_add_u32_e32 v17, v17, v4
	s_waitcnt vmcnt(9)
	v_add_u32_e32 v17, v17, v5
	s_waitcnt vmcnt(8)
	v_add_u32_e32 v17, v17, v6
	s_waitcnt vmcnt(7)
	v_add_u32_e32 v17, v17, v7
	s_waitcnt vmcnt(6)
	v_add_u32_e32 v17, v17, v8
	s_waitcnt vmcnt(5)
	v_add_u32_e32 v17, v17, v9
	s_waitcnt vmcnt(4)
	v_add_u32_e32 v17, v17, v10
	s_waitcnt vmcnt(3)
	v_add_u32_e32 v17, v17, v11
	s_waitcnt vmcnt(2)
	v_add_u32_e32 v17, v17, v12
	s_waitcnt vmcnt(1)
	v_add_u32_e32 v17, v17, v13
	s_waitcnt vmcnt(0)
	v_add_u32_e32 v17, v17, v14
	v_cmp_eq_u32_e32 vcc, s47, v17
	s_cbranch_vccnz .LBB0_167
	s_and_b32 s48, s56, 0xff
	s_cmp_eq_u32 s48, 0
	s_mov_b64 s[48:49], -1
	s_mov_b64 s[54:55], -1
	s_sleep 0
	s_cbranch_scc1 .LBB0_172
	s_and_b64 vcc, exec, s[54:55]
	s_cbranch_vccz .LBB0_167

.LBB0_186:
	s_and_b32 s24, s28, 0xff
	s_mov_b64 s[22:23], -1
	s_cmp_lg_u32 s24, 0
	s_mov_b64 s[26:27], -1
	s_sleep 0
	s_cbranch_scc0 .LBB0_189
	s_and_b64 vcc, exec, s[26:27]
	s_cbranch_vccz .LBB0_185

.LBB0_203:
	s_and_b32 s20, s26, 0xff
	s_cmp_lg_u32 s20, 0
	s_mov_b64 s[22:23], -1
	s_sleep 0
	s_cbranch_scc0 .LBB0_206
	s_mov_b64 s[24:25], -1
	s_and_b64 vcc, exec, s[22:23]
	s_cbranch_vccz .LBB0_202

.LBB0_237:
	global_load_dword v15, v16, s[10:11] sc1
	global_load_dword v0, v16, s[12:13] sc1
	global_load_dword v1, v16, s[14:15] sc1
	global_load_dword v2, v16, s[16:17] sc1
	global_load_dword v3, v16, s[18:19] sc1
	global_load_dword v4, v16, s[20:21] sc1
	global_load_dword v5, v16, s[22:23] sc1
	global_load_dword v6, v16, s[24:25] sc1
	global_load_dword v7, v16, s[26:27] sc1
	global_load_dword v8, v16, s[28:29] sc1
	global_load_dword v9, v16, s[30:31] sc1
	global_load_dword v10, v16, s[34:35] sc1
	global_load_dword v11, v16, s[36:37] sc1
	global_load_dword v12, v16, s[38:39] sc1
	global_load_dword v13, v16, s[40:41] sc1
	global_load_dword v14, v16, s[42:43] sc1
	s_mov_b64 s[48:49], -1
	s_mov_b64 s[50:51], -1
	s_waitcnt vmcnt(14)
	v_add_u32_e32 v17, v0, v15
	s_waitcnt vmcnt(13)
	v_add_u32_e32 v17, v17, v1
	s_waitcnt vmcnt(12)
	v_add_u32_e32 v17, v17, v2
	s_waitcnt vmcnt(11)
	v_add_u32_e32 v17, v17, v3
	s_waitcnt vmcnt(10)
	v_add_u32_e32 v17, v17, v4
	s_waitcnt vmcnt(9)
	v_add_u32_e32 v17, v17, v5
	s_waitcnt vmcnt(8)
	v_add_u32_e32 v17, v17, v6
	s_waitcnt vmcnt(7)
	v_add_u32_e32 v17, v17, v7
	s_waitcnt vmcnt(6)
	v_add_u32_e32 v17, v17, v8
	s_waitcnt vmcnt(5)
	v_add_u32_e32 v17, v17, v9
	s_waitcnt vmcnt(4)
	v_add_u32_e32 v17, v17, v10
	s_waitcnt vmcnt(3)
	v_add_u32_e32 v17, v17, v11
	s_waitcnt vmcnt(2)
	v_add_u32_e32 v17, v17, v12
	s_waitcnt vmcnt(1)
	v_add_u32_e32 v17, v17, v13
	s_waitcnt vmcnt(0)
	v_add_u32_e32 v17, v17, v14
	v_cmp_eq_u32_e32 vcc, s58, v17
	s_cbranch_vccnz .LBB0_236
	s_and_b32 s48, s59, 0xff
	s_cmp_eq_u32 s48, 0
	s_mov_b64 s[48:49], -1
	s_mov_b64 s[54:55], -1
	s_sleep 0
	s_cbranch_scc1 .LBB0_241
	s_and_b64 vcc, exec, s[54:55]
	s_cbranch_vccz .LBB0_236

.LBB0_272:
	s_and_b32 s22, s28, 0xff
	s_cmp_lg_u32 s22, 0
	s_mov_b64 s[24:25], -1
	s_sleep 0
	s_cbranch_scc0 .LBB0_275
	s_mov_b64 s[26:27], -1
	s_and_b64 vcc, exec, s[24:25]
	s_cbranch_vccz .LBB0_271

.LBB0_404:
	global_load_dword v15, v16, s[10:11] sc1
	global_load_dword v0, v16, s[12:13] sc1
	global_load_dword v1, v16, s[14:15] sc1
	global_load_dword v2, v16, s[16:17] sc1
	global_load_dword v3, v16, s[18:19] sc1
	global_load_dword v4, v16, s[20:21] sc1
	global_load_dword v5, v16, s[22:23] sc1
	global_load_dword v6, v16, s[24:25] sc1
	global_load_dword v7, v16, s[26:27] sc1
	global_load_dword v8, v16, s[28:29] sc1
	global_load_dword v9, v16, s[30:31] sc1
	global_load_dword v10, v16, s[34:35] sc1
	global_load_dword v11, v16, s[36:37] sc1
	global_load_dword v12, v16, s[38:39] sc1
	global_load_dword v13, v16, s[40:41] sc1
	global_load_dword v14, v16, s[42:43] sc1
	s_mov_b64 s[48:49], -1
	s_mov_b64 s[50:51], -1
	s_waitcnt vmcnt(14)
	v_add_u32_e32 v17, v0, v15
	s_waitcnt vmcnt(13)
	v_add_u32_e32 v17, v17, v1
	s_waitcnt vmcnt(12)
	v_add_u32_e32 v17, v17, v2
	s_waitcnt vmcnt(11)
	v_add_u32_e32 v17, v17, v3
	s_waitcnt vmcnt(10)
	v_add_u32_e32 v17, v17, v4
	s_waitcnt vmcnt(9)
	v_add_u32_e32 v17, v17, v5
	s_waitcnt vmcnt(8)
	v_add_u32_e32 v17, v17, v6
	s_waitcnt vmcnt(7)
	v_add_u32_e32 v17, v17, v7
	s_waitcnt vmcnt(6)
	v_add_u32_e32 v17, v17, v8
	s_waitcnt vmcnt(5)
	v_add_u32_e32 v17, v17, v9
	s_waitcnt vmcnt(4)
	v_add_u32_e32 v17, v17, v10
	s_waitcnt vmcnt(3)
	v_add_u32_e32 v17, v17, v11
	s_waitcnt vmcnt(2)
	v_add_u32_e32 v17, v17, v12
	s_waitcnt vmcnt(1)
	v_add_u32_e32 v17, v17, v13
	s_waitcnt vmcnt(0)
	v_add_u32_e32 v17, v17, v14
	v_cmp_eq_u32_e32 vcc, s54, v17
	s_cbranch_vccnz .LBB0_403
	s_and_b32 s48, s55, 0xff
	s_cmp_eq_u32 s48, 0
	s_mov_b64 s[48:49], -1
	s_mov_b64 s[58:59], -1
	s_sleep 0
	s_cbranch_scc1 .LBB0_408
	s_and_b64 vcc, exec, s[58:59]
	s_cbranch_vccz .LBB0_403

.LBB0_467:
	global_load_dword v15, v16, s[10:11] sc1
	global_load_dword v0, v16, s[12:13] sc1
	global_load_dword v1, v16, s[16:17] sc1
	global_load_dword v2, v16, s[18:19] sc1
	global_load_dword v3, v16, s[20:21] sc1
	global_load_dword v4, v16, s[22:23] sc1
	global_load_dword v5, v16, s[24:25] sc1
	global_load_dword v6, v16, s[26:27] sc1
	global_load_dword v7, v16, s[28:29] sc1
	global_load_dword v8, v16, s[30:31] sc1
	global_load_dword v9, v16, s[34:35] sc1
	global_load_dword v10, v16, s[36:37] sc1
	global_load_dword v11, v16, s[38:39] sc1
	global_load_dword v12, v16, s[40:41] sc1
	global_load_dword v13, v16, s[42:43] sc1
	global_load_dword v14, v16, s[48:49] sc1
	s_mov_b64 s[50:51], -1
	s_mov_b64 s[58:59], -1
	s_waitcnt vmcnt(14)
	v_add_u32_e32 v17, v0, v15
	s_waitcnt vmcnt(13)
	v_add_u32_e32 v17, v17, v1
	s_waitcnt vmcnt(12)
	v_add_u32_e32 v17, v17, v2
	s_waitcnt vmcnt(11)
	v_add_u32_e32 v17, v17, v3
	s_waitcnt vmcnt(10)
	v_add_u32_e32 v17, v17, v4
	s_waitcnt vmcnt(9)
	v_add_u32_e32 v17, v17, v5
	s_waitcnt vmcnt(8)
	v_add_u32_e32 v17, v17, v6
	s_waitcnt vmcnt(7)
	v_add_u32_e32 v17, v17, v7
	s_waitcnt vmcnt(6)
	v_add_u32_e32 v17, v17, v8
	s_waitcnt vmcnt(5)
	v_add_u32_e32 v17, v17, v9
	s_waitcnt vmcnt(4)
	v_add_u32_e32 v17, v17, v10
	s_waitcnt vmcnt(3)
	v_add_u32_e32 v17, v17, v11
	s_waitcnt vmcnt(2)
	v_add_u32_e32 v17, v17, v12
	s_waitcnt vmcnt(1)
	v_add_u32_e32 v17, v17, v13
	s_waitcnt vmcnt(0)
	v_add_u32_e32 v17, v17, v14
	v_cmp_eq_u32_e32 vcc, s54, v17
	s_cbranch_vccnz .LBB0_466
	s_and_b32 s50, s55, 0xff
	s_cmp_eq_u32 s50, 0
	s_mov_b64 s[50:51], -1
	s_mov_b64 s[60:61], -1
	s_sleep 0
	s_cbranch_scc1 .LBB0_471
	s_and_b64 vcc, exec, s[60:61]
	s_cbranch_vccz .LBB0_466

.LBB0_485:
	s_and_b32 s26, s30, 0xff
	s_mov_b64 s[24:25], -1
	s_cmp_lg_u32 s26, 0
	s_mov_b64 s[28:29], -1
	s_sleep 0
	s_cbranch_scc0 .LBB0_488
	s_and_b64 vcc, exec, s[28:29]
	s_cbranch_vccz .LBB0_484

.LBB0_616:
	global_load_dword v15, v16, s[12:13] sc1
	global_load_dword v0, v16, s[14:15] sc1
	global_load_dword v1, v16, s[16:17] sc1
	global_load_dword v2, v16, s[18:19] sc1
	global_load_dword v3, v16, s[20:21] sc1
	global_load_dword v4, v16, s[22:23] sc1
	global_load_dword v5, v16, s[24:25] sc1
	global_load_dword v6, v16, s[26:27] sc1
	global_load_dword v7, v16, s[28:29] sc1
	global_load_dword v8, v16, s[30:31] sc1
	global_load_dword v9, v16, s[34:35] sc1
	global_load_dword v10, v16, s[36:37] sc1
	global_load_dword v11, v16, s[38:39] sc1
	global_load_dword v12, v16, s[40:41] sc1
	global_load_dword v13, v16, s[42:43] sc1
	global_load_dword v14, v16, s[48:49] sc1
	s_mov_b64 s[50:51], -1
	s_mov_b64 s[58:59], -1
	s_waitcnt vmcnt(14)
	v_add_u32_e32 v17, v0, v15
	s_waitcnt vmcnt(13)
	v_add_u32_e32 v17, v17, v1
	s_waitcnt vmcnt(12)
	v_add_u32_e32 v17, v17, v2
	s_waitcnt vmcnt(11)
	v_add_u32_e32 v17, v17, v3
	s_waitcnt vmcnt(10)
	v_add_u32_e32 v17, v17, v4
	s_waitcnt vmcnt(9)
	v_add_u32_e32 v17, v17, v5
	s_waitcnt vmcnt(8)
	v_add_u32_e32 v17, v17, v6
	s_waitcnt vmcnt(7)
	v_add_u32_e32 v17, v17, v7
	s_waitcnt vmcnt(6)
	v_add_u32_e32 v17, v17, v8
	s_waitcnt vmcnt(5)
	v_add_u32_e32 v17, v17, v9
	s_waitcnt vmcnt(4)
	v_add_u32_e32 v17, v17, v10
	s_waitcnt vmcnt(3)
	v_add_u32_e32 v17, v17, v11
	s_waitcnt vmcnt(2)
	v_add_u32_e32 v17, v17, v12
	s_waitcnt vmcnt(1)
	v_add_u32_e32 v17, v17, v13
	s_waitcnt vmcnt(0)
	v_add_u32_e32 v17, v17, v14
	v_cmp_eq_u32_e32 vcc, s54, v17
	s_cbranch_vccnz .LBB0_615
	s_and_b32 s50, s55, 0xff
	s_cmp_eq_u32 s50, 0
	s_mov_b64 s[50:51], -1
	s_mov_b64 s[60:61], -1
	s_sleep 0
	s_cbranch_scc1 .LBB0_620
	s_and_b64 vcc, exec, s[60:61]
	s_cbranch_vccz .LBB0_615

.LBB0_926:
	s_sleep 0
	global_load_dword v2, v0, s[6:7] offset:32 sc1
	s_waitcnt vmcnt(0)
	v_and_b32_e32 v2, 0xffff0000, v2
	v_cmp_ne_u32_e32 vcc, v2, v1
	s_or_b64 s[8:9], vcc, s[8:9]
	s_andn2_b64 exec, exec, s[8:9]
	s_cbranch_execnz .LBB0_926

.LBB0_1026:
	v_mul_f32_e32 v153, v32, v186
	v_mul_f32_e32 v155, v60, v187
	v_cvt_pk_bf16_f32 v153, v153, v155
	ds_write_b32 v145, v153 offset:112
	v_mul_f32_e32 v153, v33, v186
	v_mul_f32_e32 v155, v61, v187
	v_cvt_pk_bf16_f32 v153, v153, v155
	ds_write_b32 v145, v153 offset:244
	v_mul_f32_e32 v153, v34, v186
	v_mul_f32_e32 v155, v62, v187
	v_cvt_pk_bf16_f32 v153, v153, v155
	ds_write_b32 v145, v153 offset:376
	v_mul_f32_e32 v153, v35, v186
	v_mul_f32_e32 v155, v63, v187
	v_cvt_pk_bf16_f32 v153, v153, v155
	ds_write_b32 v145, v153 offset:508
	ds_read2_b32 v[186:187], v147 offset1:1
	ds_read2_b32 v[188:189], v147 offset0:2 offset1:3
	v_mad_u64_u32 v[190:191], s[6:7], s37, v130, 0
	v_lshl_add_u64 v[190:191], v[190:191], 1, s[10:11]
	ds_read2_b32 v[194:195], v149 offset1:1
	ds_read2_b32 v[196:197], v149 offset0:2 offset1:3
	v_lshl_add_u64 v[190:191], v[190:191], 0, v[166:167]
	s_waitcnt lgkmcnt(2)
	global_store_dwordx4 v[190:191], v[186:189], off nt
	v_cmp_gt_i32_e32 vcc, s39, v170
	s_nop 0
	v_mad_u64_u32 v[186:187], s[6:7], s37, v168, 0
	v_lshl_add_u64 v[186:187], v[186:187], 1, s[10:11]
	v_lshl_add_u64 v[186:187], v[186:187], 0, v[166:167]
	s_waitcnt lgkmcnt(0)
	global_store_dwordx4 v[186:187], v[194:197], off nt
	s_and_saveexec_b64 s[6:7], vcc
	s_cbranch_execz .LBB0_1033
	v_add_u32_e32 v153, v129, v131
	ds_read2_b32 v[186:187], v153 offset1:1
	ds_read2_b32 v[188:189], v153 offset0:2 offset1:3
	v_mad_u64_u32 v[190:191], s[20:21], s37, v170, 0
	v_lshl_add_u64 v[190:191], v[190:191], 1, s[10:11]
	v_lshl_add_u64 v[190:191], v[190:191], 0, v[166:167]
	s_waitcnt lgkmcnt(0)
	global_store_dwordx4 v[190:191], v[186:189], off nt
	s_or_b64 exec, exec, s[6:7]
	v_cmp_gt_i32_e32 vcc, s39, v172
	s_and_saveexec_b64 s[6:7], vcc
	s_cbranch_execnz .LBB0_1034

.LBB0_1116:
	global_load_dword v15, v16, s[12:13] sc1
	global_load_dword v0, v16, s[16:17] sc1
	global_load_dword v1, v16, s[18:19] sc1
	global_load_dword v2, v16, s[20:21] sc1
	global_load_dword v3, v16, s[22:23] sc1
	global_load_dword v4, v16, s[24:25] sc1
	global_load_dword v5, v16, s[26:27] sc1
	global_load_dword v6, v16, s[28:29] sc1
	global_load_dword v7, v16, s[30:31] sc1
	global_load_dword v8, v16, s[34:35] sc1
	global_load_dword v9, v16, s[36:37] sc1
	global_load_dword v10, v16, s[38:39] sc1
	global_load_dword v11, v16, s[40:41] sc1
	global_load_dword v12, v16, s[42:43] sc1
	global_load_dword v13, v16, s[48:49] sc1
	global_load_dword v14, v16, s[50:51] sc1
	s_mov_b64 s[58:59], -1
	s_mov_b64 s[60:61], -1
	s_waitcnt vmcnt(14)
	v_add_u32_e32 v17, v0, v15
	s_waitcnt vmcnt(13)
	v_add_u32_e32 v17, v17, v1
	s_waitcnt vmcnt(12)
	v_add_u32_e32 v17, v17, v2
	s_waitcnt vmcnt(11)
	v_add_u32_e32 v17, v17, v3
	s_waitcnt vmcnt(10)
	v_add_u32_e32 v17, v17, v4
	s_waitcnt vmcnt(9)
	v_add_u32_e32 v17, v17, v5
	s_waitcnt vmcnt(8)
	v_add_u32_e32 v17, v17, v6
	s_waitcnt vmcnt(7)
	v_add_u32_e32 v17, v17, v7
	s_waitcnt vmcnt(6)
	v_add_u32_e32 v17, v17, v8
	s_waitcnt vmcnt(5)
	v_add_u32_e32 v17, v17, v9
	s_waitcnt vmcnt(4)
	v_add_u32_e32 v17, v17, v10
	s_waitcnt vmcnt(3)
	v_add_u32_e32 v17, v17, v11
	s_waitcnt vmcnt(2)
	v_add_u32_e32 v17, v17, v12
	s_waitcnt vmcnt(1)
	v_add_u32_e32 v17, v17, v13
	s_waitcnt vmcnt(0)
	v_add_u32_e32 v17, v17, v14
	v_cmp_eq_u32_e32 vcc, s54, v17
	s_cbranch_vccnz .LBB0_1115
	s_and_b32 s56, s55, 0xff
	s_cmp_eq_u32 s56, 0
	s_mov_b64 s[62:63], -1
	s_sleep 0
	s_cbranch_scc1 .LBB0_1120
	s_and_b64 vcc, exec, s[62:63]
	s_cbranch_vccz .LBB0_1115

.LBB0_1134:
	s_and_b32 s28, s33, 0xff
	s_mov_b64 s[26:27], -1
	s_cmp_lg_u32 s28, 0
	s_mov_b64 s[30:31], -1
	s_sleep 0
	s_cbranch_scc0 .LBB0_1137
	s_and_b64 vcc, exec, s[30:31]
	s_cbranch_vccz .LBB0_1133

.LBB0_1151:
	s_and_b32 s24, s30, 0xff
	s_cmp_lg_u32 s24, 0
	s_mov_b64 s[26:27], -1
	s_sleep 0
	s_cbranch_scc0 .LBB0_1154
	s_mov_b64 s[28:29], -1
	s_and_b64 vcc, exec, s[26:27]
	s_cbranch_vccz .LBB0_1150

.LBB0_1282:
	global_load_dword v15, v16, s[12:13] sc1
	global_load_dword v0, v16, s[16:17] sc1
	global_load_dword v1, v16, s[18:19] sc1
	global_load_dword v2, v16, s[20:21] sc1
	global_load_dword v3, v16, s[22:23] sc1
	global_load_dword v4, v16, s[24:25] sc1
	global_load_dword v5, v16, s[26:27] sc1
	global_load_dword v6, v16, s[28:29] sc1
	global_load_dword v7, v16, s[30:31] sc1
	global_load_dword v8, v16, s[34:35] sc1
	global_load_dword v9, v16, s[36:37] sc1
	global_load_dword v10, v16, s[38:39] sc1
	global_load_dword v11, v16, s[40:41] sc1
	global_load_dword v12, v16, s[42:43] sc1
	global_load_dword v13, v16, s[48:49] sc1
	global_load_dword v14, v16, s[50:51] sc1
	s_mov_b64 s[56:57], -1
	s_mov_b64 s[58:59], -1
	s_waitcnt vmcnt(14)
	v_add_u32_e32 v17, v0, v15
	s_waitcnt vmcnt(13)
	v_add_u32_e32 v17, v17, v1
	s_waitcnt vmcnt(12)
	v_add_u32_e32 v17, v17, v2
	s_waitcnt vmcnt(11)
	v_add_u32_e32 v17, v17, v3
	s_waitcnt vmcnt(10)
	v_add_u32_e32 v17, v17, v4
	s_waitcnt vmcnt(9)
	v_add_u32_e32 v17, v17, v5
	s_waitcnt vmcnt(8)
	v_add_u32_e32 v17, v17, v6
	s_waitcnt vmcnt(7)
	v_add_u32_e32 v17, v17, v7
	s_waitcnt vmcnt(6)
	v_add_u32_e32 v17, v17, v8
	s_waitcnt vmcnt(5)
	v_add_u32_e32 v17, v17, v9
	s_waitcnt vmcnt(4)
	v_add_u32_e32 v17, v17, v10
	s_waitcnt vmcnt(3)
	v_add_u32_e32 v17, v17, v11
	s_waitcnt vmcnt(2)
	v_add_u32_e32 v17, v17, v12
	s_waitcnt vmcnt(1)
	v_add_u32_e32 v17, v17, v13
	s_waitcnt vmcnt(0)
	v_add_u32_e32 v17, v17, v14
	v_cmp_eq_u32_e32 vcc, s54, v17
	s_cbranch_vccnz .LBB0_1281
	s_and_b32 s56, s55, 0xff
	s_cmp_eq_u32 s56, 0
	s_mov_b64 s[56:57], -1
	s_mov_b64 s[60:61], -1
	s_sleep 0
	s_cbranch_scc1 .LBB0_1286
	s_and_b64 vcc, exec, s[60:61]
	s_cbranch_vccz .LBB0_1281

.LBB0_1939:
	global_load_dword v15, v16, s[12:13] sc1
	global_load_dword v0, v16, s[14:15] sc1
	global_load_dword v1, v16, s[16:17] sc1
	global_load_dword v2, v16, s[18:19] sc1
	global_load_dword v3, v16, s[20:21] sc1
	global_load_dword v4, v16, s[22:23] sc1
	global_load_dword v5, v16, s[24:25] sc1
	global_load_dword v6, v16, s[26:27] sc1
	global_load_dword v7, v16, s[28:29] sc1
	global_load_dword v8, v16, s[30:31] sc1
	global_load_dword v9, v16, s[34:35] sc1
	global_load_dword v10, v16, s[36:37] sc1
	global_load_dword v11, v16, s[38:39] sc1
	global_load_dword v12, v16, s[40:41] sc1
	global_load_dword v13, v16, s[42:43] sc1
	global_load_dword v14, v16, s[48:49] sc1
	s_mov_b64 s[50:51], -1
	s_mov_b64 s[56:57], -1
	s_waitcnt vmcnt(14)
	v_add_u32_e32 v17, v0, v15
	s_waitcnt vmcnt(13)
	v_add_u32_e32 v17, v17, v1
	s_waitcnt vmcnt(12)
	v_add_u32_e32 v17, v17, v2
	s_waitcnt vmcnt(11)
	v_add_u32_e32 v17, v17, v3
	s_waitcnt vmcnt(10)
	v_add_u32_e32 v17, v17, v4
	s_waitcnt vmcnt(9)
	v_add_u32_e32 v17, v17, v5
	s_waitcnt vmcnt(8)
	v_add_u32_e32 v17, v17, v6
	s_waitcnt vmcnt(7)
	v_add_u32_e32 v17, v17, v7
	s_waitcnt vmcnt(6)
	v_add_u32_e32 v17, v17, v8
	s_waitcnt vmcnt(5)
	v_add_u32_e32 v17, v17, v9
	s_waitcnt vmcnt(4)
	v_add_u32_e32 v17, v17, v10
	s_waitcnt vmcnt(3)
	v_add_u32_e32 v17, v17, v11
	s_waitcnt vmcnt(2)
	v_add_u32_e32 v17, v17, v12
	s_waitcnt vmcnt(1)
	v_add_u32_e32 v17, v17, v13
	s_waitcnt vmcnt(0)
	v_add_u32_e32 v17, v17, v14
	v_cmp_eq_u32_e32 vcc, s54, v17
	s_cbranch_vccnz .LBB0_1938
	s_and_b32 s50, s55, 0xff
	s_cmp_eq_u32 s50, 0
	s_mov_b64 s[50:51], -1
	s_mov_b64 s[58:59], -1
	s_sleep 0
	s_cbranch_scc1 .LBB0_1943
	s_and_b64 vcc, exec, s[58:59]
	s_cbranch_vccz .LBB0_1938

.LBB0_2038:
	global_load_dword v15, v16, s[12:13] sc1
	global_load_dword v0, v16, s[14:15] sc1
	global_load_dword v1, v16, s[16:17] sc1
	global_load_dword v2, v16, s[18:19] sc1
	global_load_dword v3, v16, s[20:21] sc1
	global_load_dword v4, v16, s[22:23] sc1
	global_load_dword v5, v16, s[24:25] sc1
	global_load_dword v6, v16, s[26:27] sc1
	global_load_dword v7, v16, s[28:29] sc1
	global_load_dword v8, v16, s[30:31] sc1
	global_load_dword v9, v16, s[34:35] sc1
	global_load_dword v10, v16, s[36:37] sc1
	global_load_dword v11, v16, s[38:39] sc1
	global_load_dword v12, v16, s[40:41] sc1
	global_load_dword v13, v16, s[42:43] sc1
	global_load_dword v14, v16, s[44:45] sc1
	s_mov_b64 s[48:49], -1
	s_mov_b64 s[50:51], -1
	s_waitcnt vmcnt(14)
	v_add_u32_e32 v17, v0, v15
	s_waitcnt vmcnt(13)
	v_add_u32_e32 v17, v17, v1
	s_waitcnt vmcnt(12)
	v_add_u32_e32 v17, v17, v2
	s_waitcnt vmcnt(11)
	v_add_u32_e32 v17, v17, v3
	s_waitcnt vmcnt(10)
	v_add_u32_e32 v17, v17, v4
	s_waitcnt vmcnt(9)
	v_add_u32_e32 v17, v17, v5
	s_waitcnt vmcnt(8)
	v_add_u32_e32 v17, v17, v6
	s_waitcnt vmcnt(7)
	v_add_u32_e32 v17, v17, v7
	s_waitcnt vmcnt(6)
	v_add_u32_e32 v17, v17, v8
	s_waitcnt vmcnt(5)
	v_add_u32_e32 v17, v17, v9
	s_waitcnt vmcnt(4)
	v_add_u32_e32 v17, v17, v10
	s_waitcnt vmcnt(3)
	v_add_u32_e32 v17, v17, v11
	s_waitcnt vmcnt(2)
	v_add_u32_e32 v17, v17, v12
	s_waitcnt vmcnt(1)
	v_add_u32_e32 v17, v17, v13
	s_waitcnt vmcnt(0)
	v_add_u32_e32 v17, v17, v14
	v_cmp_eq_u32_e32 vcc, s47, v17
	s_cbranch_vccnz .LBB0_2037
	s_and_b32 s48, s54, 0xff
	s_cmp_eq_u32 s48, 0
	s_mov_b64 s[48:49], -1
	s_mov_b64 s[52:53], -1
	s_sleep 0
	s_cbranch_scc1 .LBB0_2042
	s_and_b64 vcc, exec, s[52:53]
	s_cbranch_vccz .LBB0_2037
